# also the grid barrier in front of the mixer: closing s_barrier moved down to the first Z load (parameter warm-up loads and address set-up run before it)
# speedup vs baseline: 1.0089x; 1.0087x over previous
; __device__ __forceinline__ void attn_unit(const Args& A, int l, int n, int kvh, const bf16* Z, bf16* MIX, ss_t* ssb, unsigned char* lds, int tid, int wid, int lane) {
;     bf16* KS = (bf16*)(lds + LDS_KS); bf16* VT = (bf16*)(lds + LDS_VT); float* BT = (float*)(lds + LDS_BT);
;     const float* gk = A.k_norm_g + l * 64; const float* gq = A.q_norm_g + l * 64;
; #pragma unroll
;     for (int i = 0; i < 4; ++i) {
;         const int id = tid + 512 * i, row = id >> 3, ch = id & 7; const int tok = (n - 1) * 128 + row;
;         u32x4 kw = (u32x4){0u, 0u, 0u, 0u}, vw = (u32x4){0u, 0u, 0u, 0u};
;         if (tok >= 0) { const bf16* zr = Z + (size_t)tok * INW; kw = *(const u32x4*)(zr + KCOL + kvh * 64 + ch * 8); vw = *(const u32x4*)(zr + VCOL + kvh * 64 + ch * 8); }
;         float f[8]; float ss = 0.f;
; #pragma unroll
;         for (int e = 0; e < 4; ++e) { f[2 * e] = bflo(kw[e]); f[2 * e + 1] = bfhi(kw[e]); ss += f[2 * e] * f[2 * e] + f[2 * e + 1] * f[2 * e + 1]; }
;         ss += __shfl_xor(ss, 1); ss += __shfl_xor(ss, 2); ss += __shfl_xor(ss, 4);
;         const float rstd = 1.0f / sqrtf(ss * (1.0f / 64.f) + EPS);
;         const f32x4 g0 = *(const f32x4*)(gk + ch * 8), g1 = *(const f32x4*)(gk + ch * 8 + 4);
;         u32x4 o; o.x = pkbf(f[0] * rstd * g0.x, f[1] * rstd * g0.y); o.y = pkbf(f[2] * rstd * g0.z, f[3] * rstd * g0.w); o.z = pkbf(f[4] * rstd * g1.x, f[5] * rstd * g1.y); o.w = pkbf(f[6] * rstd * g1.z, f[7] * rstd * g1.w);
;         *(u32x4*)(KS + row * KS_STRIDE + ch * 8) = o;
; #pragma unroll
;         for (int e = 0; e < 4; ++e) { VT[(ch * 8 + 2 * e) * VT_STRIDE + row] = (bf16)(vw[e] & 0xffffu); VT[(ch * 8 + 2 * e + 1) * VT_STRIDE + row] = (bf16)(vw[e] >> 16); }
;     }
;     { const int g = tid >> 7, dist = tid & 127; BT[g * 128 + dist] = A.rel_bias[t5_bucket(dist) * 16 + kvh * 4 + g] * 1.4426950408889634f; }
; __global__ void __launch_bounds__(NWAVES * 64, 2) fwd_kernel(Args A) {
;     ...
;         { PHASE_IDS();
;           if (G == 256) mixer_phase256(A, l, vc, Z, MIX, SS + (size_t)(SS_A + l) * SEQ, SS + (size_t)(SS_B + l) * SEQ, lds, tid, wid, lane);
;           else {
;             for (int a = bx; a < 256; a += G) attn_unit(A, l, a >> 2, a & 3, Z, MIX, SS + (size_t)(SS_B + l) * SEQ, lds, tid, wid, lane);
;             for (int s = bx; s < 1024; s += G) sgu_unit(A, l, s >> 4, s & 15, Z, MIX, SS + (size_t)(SS_A + l) * SEQ, lds, tid, wid, lane); } }
.LBB0_301:
	s_or_b64 exec, exec, s[2:3]
	v_readlane_b32 s4, v250, 10
	v_readlane_b32 s5, v250, 11
	s_andn2_b64 vcc, exec, s[4:5]
	v_readlane_b32 s4, v249, 59
	v_readlane_b32 s5, v249, 60
	v_mov_b32_e32 v113, v204
	s_waitcnt lgkmcnt(0)
	v_cndmask_b32_e64 v0, 0, 1, s[4:5]
	v_cmp_ne_u32_e64 s[4:5], 1, v0
	v_readfirstlane_b32 s17, v113
	v_and_b32_e32 v174, 63, v113
	s_ashr_i32 s73, s17, 6
	s_mov_b64 s[2:3], -1
	v_writelane_b32 v247, s4, 31
	s_nop 1
	v_writelane_b32 v247, s5, 32
	s_cbranch_vccnz .LBB0_505
	s_barrier
	v_writelane_b32 v247, s17, 33
	v_writelane_b32 v247, s73, 34
	v_writelane_b32 v247, s81, 35
	v_writelane_b32 v247, s78, 36
	v_lshlrev_b32_e32 v0, 3, v113
	v_add_u32_e32 v1, 0x200, v113
	v_writelane_b32 v247, s79, 37
	s_mov_b32 s39, s77
	v_readlane_b32 s2, v247, 31
	v_readlane_b32 s3, v247, 32
	s_and_b64 vcc, exec, s[2:3]
	v_ashrrev_i32_e32 v31, 3, v113
	v_and_b32_e32 v26, 56, v0
	v_ashrrev_i32_e32 v50, 3, v1
	s_cbranch_vccnz .LBB0_457
	v_and_b32_e32 v1, 64, v208
	v_readlane_b32 s26, v247, 36
	v_xor_b32_e32 v0, 1, v208
	v_add_u32_e32 v3, 64, v1
	s_mov_b32 s7, s39
	s_lshl_b32 s6, s26, 13
	v_cmp_lt_i32_e32 vcc, v0, v3
	s_lshl_b64 s[2:3], s[6:7], 3
	v_readlane_b32 s4, v247, 30
	v_cndmask_b32_e32 v0, v208, v0, vcc
	s_add_u32 s2, s4, s2
	v_readlane_b32 s4, v250, 46
	v_lshlrev_b32_e32 v27, 2, v0
	v_xor_b32_e32 v0, 2, v208
	s_addc_u32 s3, s4, s3
	v_cmp_lt_i32_e32 vcc, v0, v3
	s_add_u32 s4, s2, 0xc0000
	s_addc_u32 s5, s3, 0
	v_cndmask_b32_e32 v0, v208, v0, vcc
	s_lshl_b32 s6, s26, 6
	v_lshlrev_b32_e32 v48, 2, v0
	v_xor_b32_e32 v0, 4, v208
	s_lshl_b64 s[6:7], s[6:7], 2
	v_readlane_b32 s8, v250, 30
	v_cmp_lt_i32_e32 vcc, v0, v3
	v_readlane_b32 s9, v250, 31
	s_add_u32 s2, s8, s6
	v_cndmask_b32_e32 v0, v208, v0, vcc
	s_addc_u32 s3, s9, s7
	v_lshlrev_b32_e32 v49, 2, v0
	v_lshlrev_b32_e32 v0, 2, v26
	v_mov_b32_e32 v1, v2
	v_and_b32_e32 v10, 0x7f, v113
	v_lshl_add_u64 v[28:29], s[2:3], 0, v[0:1]
	v_lshl_add_u32 v6, v26, 1, 0
	s_movk_i32 s2, 0x20e
	v_cvt_f32_ubyte0_e32 v5, v10
	v_mad_u32_u24 v4, v26, s2, v6
	v_mul_f32_e32 v5, 0x3d800000, v5
	s_mov_b32 s2, 0x800000
	v_cmp_gt_f32_e32 vcc, s2, v5
	s_mov_b32 s2, 0x3f317217
	s_mov_b32 s8, 0x40051592
	v_cndmask_b32_e64 v11, 0, 32, vcc
	v_ldexp_f32 v5, v5, v11
	v_log_f32_e32 v5, v5
	v_mul_u32_u24_e32 v1, 0x108, v26
	v_lshlrev_b32_e32 v0, 1, v31
	v_lshlrev_b32_e32 v1, 1, v1
	v_mul_f32_e32 v11, 0x3f317217, v5
	v_fma_f32 v11, v5, s2, -v11
	v_fmac_f32_e32 v11, 0x3377d1cf, v5
	s_mov_b32 s2, 0x7f800000
	v_fmac_f32_e32 v11, 0x3f317217, v5
	v_cmp_lt_f32_e64 s[2:3], |v5|, s2
	v_add3_u32 v51, 0, v0, v1
	v_add_u32_e32 v52, v4, v0
	v_cndmask_b32_e64 v5, v5, v11, s[2:3]
	v_cndmask_b32_e32 v11, 0, v209, vcc
	v_sub_f32_e32 v5, v5, v11
	v_div_scale_f32 v11, s[2:3], s8, s8, v5
	v_rcp_f32_e32 v12, v11
	v_lshlrev_b32_e32 v0, 1, v50
	v_add3_u32 v53, 0, v0, v1
	v_add_u32_e32 v54, v4, v0
	v_fma_f32 v14, -v11, v12, 1.0
	v_fmac_f32_e32 v12, v14, v12
	v_div_scale_f32 v14, vcc, v5, s8, v5
	v_mul_f32_e32 v15, v14, v12
	v_fma_f32 v16, -v11, v15, v14
	v_fmac_f32_e32 v15, v16, v12
	v_fma_f32 v11, -v11, v15, v14
	v_div_fmas_f32 v11, v11, v12, v15
	v_add_u32_e32 v0, 0x400, v113
	v_div_fixup_f32 v5, v11, s8, v5
	v_ashrrev_i32_e32 v55, 3, v0
	v_mul_f32_e32 v5, 0x41800000, v5
	v_lshlrev_b32_e32 v0, 1, v55
	v_cvt_i32_f32_e32 v5, v5
	v_add3_u32 v56, 0, v0, v1
	v_add_u32_e32 v57, v4, v0
	v_add_u32_e32 v0, 0x600, v113
	v_ashrrev_i32_e32 v58, 3, v0
	v_lshlrev_b32_e32 v0, 1, v58
	v_add3_u32 v59, 0, v0, v1
	v_add_u32_e32 v60, v4, v0
	v_min_i32_e32 v0, 15, v5
	v_add_u32_e32 v12, 16, v0
	v_lshrrev_b32_e32 v0, 1, v113
	v_readlane_b32 s10, v250, 32
	v_readlane_b32 s11, v250, 33
	v_readlane_b32 s12, v250, 34
	v_readlane_b32 s13, v250, 35
	v_readlane_b32 s14, v250, 36
	v_readlane_b32 s15, v250, 37
	v_readlane_b32 s16, v250, 38
	v_readlane_b32 s17, v250, 39
	v_readlane_b32 s18, v250, 40
	v_readlane_b32 s19, v250, 41
	v_readlane_b32 s20, v250, 42
	v_readlane_b32 s21, v250, 43
	v_readlane_b32 s22, v250, 44
	v_readlane_b32 s23, v250, 45
	v_readlane_b32 s25, v247, 34
	v_and_b32_e32 v30, 24, v0
	v_xor_b32_e32 v0, 16, v208
	s_lshl_b32 s74, s25, 5
	v_readlane_b32 s8, v250, 12
	v_cmp_lt_i32_e32 vcc, v0, v3
	v_readlane_b32 s27, v247, 37
	s_andn2_b32 s74, s74, 63
	v_readlane_b32 s22, v250, 26
	v_cndmask_b32_e32 v0, v208, v0, vcc
	v_readlane_b32 s27, v247, 33
	v_readlane_b32 s23, v250, 27
	s_add_u32 s2, s22, s6
	v_lshrrev_b32_e32 v14, 4, v174
	v_lshlrev_b32_e32 v64, 2, v0
	v_xor_b32_e32 v0, 32, v208
	v_and_b32_e32 v62, 15, v113
	s_addc_u32 s3, s23, s7
	s_ashr_i32 s75, s27, 7
	v_cmp_lt_i32_e32 vcc, v0, v3
	v_lshlrev_b32_e32 v3, 2, v14
	v_readlane_b32 s24, v247, 24
	s_lshl_b32 s6, s75, 9
	v_lshlrev_b32_e32 v4, 5, v14
	v_mov_b32_e32 v5, v2
	v_sub_u32_e32 v3, v3, v62
	s_add_i32 s6, s24, s6
	s_lshl_b32 s7, s25, 2
	v_lshl_add_u64 v[32:33], s[2:3], 0, v[4:5]
	v_sub_u32_e32 v4, -3, v3
	s_lshl_b32 s76, s26, 4
	s_and_b32 s77, s7, 4
	v_cndmask_b32_e32 v0, v208, v0, vcc
	v_lshl_add_u32 v66, v4, 2, s6
	v_and_b32_e32 v4, 48, v174
	v_cmp_gt_u32_e32 vcc, 16, v10
	v_readlane_b32 s2, v248, 59
	v_mul_lo_u32 v7, v31, s33
	v_mul_lo_u32 v8, v50, s33
	v_mul_lo_u32 v9, v55, s33
	v_mul_lo_u32 v13, v58, s33
	v_ashrrev_i32_e32 v11, 7, v113
	v_lshlrev_b32_e32 v65, 2, v0
	v_lshlrev_b32_e32 v0, 3, v14
	v_mov_b32_e32 v1, v2
	v_add_u32_e32 v67, 0, v4
	v_cmp_lt_i32_e64 s[62:63], 0, v3
	v_cmp_lt_i32_e64 s[40:41], -1, v3
	v_cmp_lt_i32_e64 s[42:43], -2, v3
	v_cmp_lt_i32_e64 s[44:45], -3, v3
	v_or_b32_e32 v69, 48, v174
	v_cmp_gt_i32_e64 s[46:47], 1, v3
	v_cmp_gt_i32_e64 s[48:49], 0, v3
	v_cmp_gt_i32_e64 s[50:51], -1, v3
	v_cmp_gt_i32_e64 s[52:53], -2, v3
	s_bitcmp1_b32 s25, 0
	v_cndmask_b32_e32 v3, v12, v10, vcc
	v_readlane_b32 s3, v248, 60
	v_lshl_add_u32 v61, v113, 2, s24
	v_and_or_b32 v63, s27, 64, v62
	v_or_b32_e32 v68, 32, v62
	v_or_b32_e32 v70, 64, v62
	v_or_b32_e32 v71, 0x50, v62
	v_or_b32_e32 v72, 0x60, v62
	v_or_b32_e32 v73, 0x70, v174
	v_sub_u32_e32 v74, v67, v0
	v_mul_u32_u24_e32 v75, 0x210, v62
	v_mul_u32_u24_e32 v76, 0x210, v69
	v_cmp_gt_u32_e64 s[54:55], 16, v174
	v_or_b32_e32 v77, 16, v62
	s_cselect_b64 s[6:7], -1, 0
	v_lshl_add_u32 v78, v3, 4, v11
	v_lshl_add_u64 v[34:35], s[2:3], 0, v[0:1]
	v_add_u32_e32 v79, v6, v7
	v_add_u32_e32 v80, v6, v8
	v_add_u32_e32 v81, v6, v9
	v_add_u32_e32 v82, v6, v13
	v_readlane_b32 s78, v250, 0
	v_readlane_b32 s9, v250, 13
	v_readlane_b32 s10, v250, 14
	v_readlane_b32 s11, v250, 15
	v_readlane_b32 s12, v250, 16
	v_readlane_b32 s13, v250, 17
	v_readlane_b32 s14, v250, 18
	v_readlane_b32 s15, v250, 19
	v_readlane_b32 s16, v250, 20
	v_readlane_b32 s17, v250, 21
	v_readlane_b32 s18, v250, 22
	v_readlane_b32 s19, v250, 23
	v_readlane_b32 s20, v250, 24
	v_readlane_b32 s21, v250, 25
	s_branch .LBB0_305

; __device__ __forceinline__ void mixer_phase256(const Args& A, int l, int vc, const bf16* Z, bf16* MIX, ss_t* ssa, ss_t* ssb, unsigned char* lds, int tid, int wid, int lane) {
;     ...
;     const int fr = lane & 15, fq = lane >> 4;
;     const bool isK = tid < 256; const int arow = tid & 255; const int atok = (n - 1) * 128 + arow;
;     u32x4 aw[8], sw[8];
;     { const bf16* ap = Z + (size_t)(atok < 0 ? 0 : atok) * INW + (isK ? KCOL : VCOL) + kvh * 64;
; #pragma unroll
;       for (int c = 0; c < 8; ++c) aw[c] = *(const u32x4*)(ap + 8 * c); }
;     const int srow = tid & 127, sj = tid >> 7;
;     { const bf16* sp = Z + (size_t)((cb + sj) * 128 + srow) * INW + 1024 + h * 64;
; #pragma unroll
;       for (int c = 0; c < 8; ++c) sw[c] = *(const u32x4*)(sp + 8 * c); }
;     const int st = 16 * wid + fr; const int nks = (wid >> 1) + 1;
;     const float* wrow = A.sgu_w + ((size_t)(l * 16 + h) * 128 + st) * 128;
;     f32x4 wa[4][2];
; #pragma unroll
;     for (int ks = 0; ks < 4; ++ks) { wa[ks][0] = (f32x4){0.f, 0.f, 0.f, 0.f}; wa[ks][1] = wa[ks][0];
;         if (ks < nks) { wa[ks][0] = *(const f32x4*)(wrow + 32 * ks + 8 * fq); wa[ks][1] = *(const f32x4*)(wrow + 32 * ks + 8 * fq + 4); } }
.LBB0_505:
	s_and_b64 vcc, exec, s[2:3]
	s_cbranch_vccz .LBB0_803
	v_lshlrev_b32_e32 v253, 2, v174
	v_lshlrev_b32_e32 v251, 2, v113
	s_lshl_b32 s2, s78, 8
	v_readlane_b32 s100, v250, 30
	v_readlane_b32 s101, v250, 31
	v_readlane_b32 s3, v248, 3
	s_nop 0
	s_add_u32 s100, s100, s2
	s_addc_u32 s101, s101, 0
	s_nop 0
	global_load_dword v254, v253, s[100:101]
	v_readlane_b32 s100, v250, 26
	v_readlane_b32 s101, v250, 27
	s_nop 0
	s_add_u32 s100, s100, s2
	s_addc_u32 s101, s101, 0
	s_nop 0
	global_load_dword v254, v253, s[100:101]
	s_lshl_b32 s2, s78, 4
	s_or_b32 s2, s2, s3
	s_lshl_b32 s2, s2, 8
	v_readlane_b32 s100, v250, 20
	v_readlane_b32 s101, v250, 21
	s_nop 0
	s_add_u32 s100, s100, s2
	s_addc_u32 s101, s101, 0
	s_nop 0
	global_load_dword v254, v253, s[100:101]
	v_readlane_b32 s100, v250, 14
	v_readlane_b32 s101, v250, 15
	s_nop 4
	global_load_dword v254, v251, s[100:101]
	v_readlane_b32 s100, v250, 32
	v_readlane_b32 s101, v250, 33
	s_nop 4
	global_load_dword v254, v253, s[100:101]
	v_and_b32_e32 v178, 0xff, v113
	v_readlane_b32 s2, v248, 2
	v_mov_b64_e32 v[0:1], s[82:83]
	v_mov_b32_e32 v5, v2
	v_add_u32_e32 v100, s2, v178
	v_max_i32_e32 v3, 0, v100
	v_mad_u64_u32 v[0:1], s[2:3], v3, s85, v[0:1]
	s_movk_i32 s2, 0x100
	s_nop 0
	v_cmp_gt_i32_e32 vcc, s2, v113
	v_readlane_b32 s2, v247, 25
	v_readlane_b32 s3, v247, 26
	v_cndmask_b32_e32 v4, v210, v211, vcc
	v_lshl_add_u64 v[0:1], v[0:1], 0, v[4:5]
	s_mov_b32 s4, s2
	s_mov_b32 s5, s77
	v_writelane_b32 v247, s2, 25
	v_lshl_add_u64 v[0:1], v[0:1], 0, s[4:5]
	v_ashrrev_i32_e32 v177, 7, v113
	v_writelane_b32 v247, s3, 26
	v_readlane_b32 s2, v248, 6
	s_barrier
	global_load_dwordx4 v[76:79], v[0:1], off offset:48
	global_load_dwordx4 v[80:83], v[0:1], off offset:32
	global_load_dwordx4 v[84:87], v[0:1], off offset:16
	global_load_dwordx4 v[88:91], v[0:1], off
	global_load_dwordx4 v[92:95], v[0:1], off offset:112
	global_load_dwordx4 v[96:99], v[0:1], off offset:96
	global_load_dwordx4 v[68:71], v[0:1], off offset:80
	global_load_dwordx4 v[72:75], v[0:1], off offset:64
	v_add_u32_e32 v0, s2, v177
	v_readlane_b32 s2, v248, 4
	v_and_b32_e32 v3, 0x7f, v113
	v_readlane_b32 s3, v248, 5
	v_lshl_or_b32 v4, v0, 7, v3
	s_lshl_b32 s37, s78, 4
	v_mov_b64_e32 v[0:1], s[2:3]
	v_mad_i64_i32 v[0:1], s[2:3], v4, s85, v[0:1]
	global_load_dwordx4 v[44:47], v[0:1], off offset:2096
	global_load_dwordx4 v[48:51], v[0:1], off offset:2080
	global_load_dwordx4 v[52:55], v[0:1], off offset:2064
	global_load_dwordx4 v[56:59], v[0:1], off offset:2048
	global_load_dwordx4 v[60:63], v[0:1], off offset:2160
	global_load_dwordx4 v[64:67], v[0:1], off offset:2144
	global_load_dwordx4 v[4:7], v[0:1], off offset:2128
	global_load_dwordx4 v[8:11], v[0:1], off offset:2112
	v_readlane_b32 s4, v248, 3
	s_or_b32 s38, s37, s4
	v_and_b32_e32 v175, 15, v113
	s_ashr_i32 s36, s17, 7
	s_lshl_b32 s4, s38, 16
	v_lshl_or_b32 v114, s73, 4, v175
	s_add_u32 s4, s50, s4
	v_ashrrev_i32_e32 v115, 31, v114
	s_addc_u32 s5, s51, 0
	v_lshrrev_b32_e32 v176, 4, v174
	v_lshlrev_b64 v[0:1], 9, v[114:115]
	s_cmp_gt_i32 s36, -1
	s_movk_i32 s2, 0xff
	v_lshl_add_u64 v[0:1], s[4:5], 0, v[0:1]
	v_lshlrev_b32_e32 v12, 5, v176
	v_mov_b32_e32 v13, v2
	s_cselect_b64 s[8:9], -1, 0
	v_cmp_lt_i32_e64 s[2:3], s2, v113
	v_lshl_add_u64 v[0:1], v[0:1], 0, v[12:13]
	v_mov_b32_e32 v16, 0
	s_and_b64 vcc, exec, s[8:9]
	v_mov_b32_e32 v40, 0
	v_mov_b32_e32 v41, 0
	v_mov_b32_e32 v42, 0
	v_mov_b32_e32 v43, 0
	v_mov_b32_e32 v36, 0
	v_mov_b32_e32 v37, 0
	v_mov_b32_e32 v38, 0
	v_mov_b32_e32 v39, 0
	s_cbranch_vccz .LBB0_508
	global_load_dwordx4 v[40:43], v[0:1], off
	global_load_dwordx4 v[36:39], v[0:1], off offset:16
